# band attention: QK^T K-fragment ds_reads pipelined 4 deep (same edit as DSA)
# baseline (speedup 1.0000x reference)
; #define LAS __attribute__((address_space(3)))
; DEVI void qkt(f32x16& p0, f32x16& p1, LAS const unsigned char* Ks, const bf16x8* qr, int r32, int hi) {
;     p0 = (f32x16){0.f, 0.f, 0.f, 0.f, 0.f, 0.f, 0.f, 0.f, 0.f, 0.f, 0.f, 0.f, 0.f, 0.f, 0.f, 0.f}; p1 = p0;
; #pragma unroll
;     for (int d0 = 0; d0 < 8; ++d0) { const int cb = (d0 * 16 + hi * 8) * 2;
;         const bf16x8 b0 = *(LAS const bf16x8*)(Ks + FA_KSWZ(r32, cb));
;         const bf16x8 b1 = *(LAS const bf16x8*)(Ks + FA_KSWZ(32 + r32, cb));
;         p0 = __builtin_amdgcn_mfma_f32_32x32x16_bf16(b0, qr[d0], p0, 0, 0, 0);
;         p1 = __builtin_amdgcn_mfma_f32_32x32x16_bf16(b1, qr[d0], p1, 0, 0, 0); }
; template <int MODE>
; DEVI void attn_unit(LAS unsigned char* lds, const bf16_t* Qw, int ldq, const bf16_t* Kb, const bf16_t* Vb, int ldk, bf16_t* Ow, int ldo,
;                     int j_first, int ntiles, int jstep, int wj_lo, int wj_hi, int t0) {
;     ...
;                 if constexpr (MODE == M_BAND) {
;                     const int cw = t0 >> 6;
;                     if (j <= cw - 3) { const float bc = bias2[191];
; #pragma unroll
;                         for (int r = 0; r < 16; ++r) { p0[r] = fmaf(p0[r], C2, bc); p1[r] = fmaf(p1[r], C2, bc); }
.LBB11_1289:
	s_waitcnt lgkmcnt(0)
	s_barrier
	v_cmp_ge_i32_e64 s[4:5], s19, v230
	v_cmp_le_i32_e64 s[6:7], s19, v229
	s_and_b64 s[4:5], s[4:5], s[6:7]
	s_and_saveexec_b64 s[6:7], s[4:5]
	s_cbranch_execz .LBB11_1286
	v_add_u32_e32 v2, s20, v231
	v_cmp_le_i32_e64 s[4:5], s19, v240
	v_add_u32_e32 v86, v2, v232
	ds_read_b128 v[70:73], v86 offset:32768
	ds_read_b128 v[74:77], v86 offset:40960
	v_add_u32_e32 v87, v2, v233
	ds_read_b128 v[78:81], v87 offset:32768
	ds_read_b128 v[82:85], v87 offset:40960
	s_waitcnt lgkmcnt(3)
	v_mfma_f32_32x32x16_bf16 v[118:133], v[70:73], v[162:165], 0
	v_add_u32_e32 v88, v2, v234
	ds_read_b128 v[70:73], v88 offset:32768
	s_waitcnt lgkmcnt(3)
	v_mfma_f32_32x32x16_bf16 v[102:117], v[74:77], v[162:165], 0
	ds_read_b128 v[74:77], v88 offset:40960
	s_waitcnt lgkmcnt(3)
	v_mfma_f32_32x32x16_bf16 v[118:133], v[78:81], v[154:157], v[118:133]
	v_add_u32_e32 v89, v2, v235
	ds_read_b128 v[78:81], v89 offset:32768
	s_waitcnt lgkmcnt(3)
	v_mfma_f32_32x32x16_bf16 v[102:117], v[82:85], v[154:157], v[102:117]
	ds_read_b128 v[82:85], v89 offset:40960
	s_waitcnt lgkmcnt(3)
	v_mfma_f32_32x32x16_bf16 v[118:133], v[70:73], v[150:153], v[118:133]
	v_add_u32_e32 v86, v2, v236
	ds_read_b128 v[70:73], v86 offset:32768
	s_waitcnt lgkmcnt(3)
	v_mfma_f32_32x32x16_bf16 v[102:117], v[74:77], v[150:153], v[102:117]
	ds_read_b128 v[74:77], v86 offset:40960
	s_waitcnt lgkmcnt(3)
	v_mfma_f32_32x32x16_bf16 v[118:133], v[78:81], v[146:149], v[118:133]
	v_add_u32_e32 v87, v2, v237
	ds_read_b128 v[78:81], v87 offset:32768
	s_waitcnt lgkmcnt(3)
	v_mfma_f32_32x32x16_bf16 v[102:117], v[82:85], v[146:149], v[102:117]
	ds_read_b128 v[82:85], v87 offset:40960
	s_waitcnt lgkmcnt(3)
	v_mfma_f32_32x32x16_bf16 v[118:133], v[70:73], v[142:145], v[118:133]
	v_add_u32_e32 v88, v2, v238
	ds_read_b128 v[70:73], v88 offset:32768
	s_waitcnt lgkmcnt(3)
	v_mfma_f32_32x32x16_bf16 v[102:117], v[74:77], v[142:145], v[102:117]
	ds_read_b128 v[74:77], v88 offset:40960
	s_waitcnt lgkmcnt(3)
	v_mfma_f32_32x32x16_bf16 v[118:133], v[78:81], v[138:141], v[118:133]
	v_add_u32_e32 v89, v2, v239
	ds_read_b128 v[78:81], v89 offset:32768
	s_waitcnt lgkmcnt(3)
	v_mfma_f32_32x32x16_bf16 v[102:117], v[82:85], v[138:141], v[102:117]
	ds_read_b128 v[82:85], v89 offset:40960
	s_waitcnt lgkmcnt(3)
	v_mfma_f32_32x32x16_bf16 v[118:133], v[70:73], v[134:137], v[118:133]
	s_waitcnt lgkmcnt(2)
	v_mfma_f32_32x32x16_bf16 v[102:117], v[74:77], v[134:137], v[102:117]
	s_waitcnt lgkmcnt(1)
	v_mfma_f32_32x32x16_bf16 v[118:133], v[78:81], v[158:161], v[118:133]
	s_waitcnt lgkmcnt(0)
	v_mfma_f32_32x32x16_bf16 v[102:117], v[82:85], v[158:161], v[102:117]
	s_and_saveexec_b64 s[20:21], s[4:5]
	s_xor_b64 s[4:5], exec, s[20:21]
	s_cbranch_execz .LBB11_1292
	v_readlane_b32 s19, v252, 14
	s_nop 1
	v_mov_b32_e32 v2, s19
	ds_read_b32 v2, v2
	s_waitcnt lgkmcnt(0)
	s_nop 0
	v_pk_fma_f32 v[84:85], v[132:133], s[0:1], v[2:3] op_sel_hi:[1,0,0]
	v_pk_fma_f32 v[82:83], v[130:131], s[0:1], v[2:3] op_sel_hi:[1,0,0]
	v_pk_fma_f32 v[80:81], v[128:129], s[0:1], v[2:3] op_sel_hi:[1,0,0]
	v_pk_fma_f32 v[78:79], v[126:127], s[0:1], v[2:3] op_sel_hi:[1,0,0]
	v_pk_fma_f32 v[76:77], v[124:125], s[0:1], v[2:3] op_sel_hi:[1,0,0]
	v_pk_fma_f32 v[74:75], v[122:123], s[0:1], v[2:3] op_sel_hi:[1,0,0]
	v_pk_fma_f32 v[72:73], v[120:121], s[0:1], v[2:3] op_sel_hi:[1,0,0]
	v_pk_fma_f32 v[70:71], v[118:119], s[0:1], v[2:3] op_sel_hi:[1,0,0]
	v_pk_fma_f32 v[100:101], v[116:117], s[0:1], v[2:3] op_sel_hi:[1,0,0]
	v_pk_fma_f32 v[98:99], v[114:115], s[0:1], v[2:3] op_sel_hi:[1,0,0]
	v_pk_fma_f32 v[96:97], v[112:113], s[0:1], v[2:3] op_sel_hi:[1,0,0]
	v_pk_fma_f32 v[94:95], v[110:111], s[0:1], v[2:3] op_sel_hi:[1,0,0]
	v_pk_fma_f32 v[92:93], v[108:109], s[0:1], v[2:3] op_sel_hi:[1,0,0]
	v_pk_fma_f32 v[90:91], v[106:107], s[0:1], v[2:3] op_sel_hi:[1,0,0]
	v_pk_fma_f32 v[88:89], v[104:105], s[0:1], v[2:3] op_sel_hi:[1,0,0]
	v_pk_fma_f32 v[86:87], v[102:103], s[0:1], v[2:3] op_sel_hi:[1,0,0]
